# attention QK segment: K fragments through a ring of three register quads (reads issued three MFMAs ahead)
# speedup vs baseline: 1.0010x; 1.0010x over previous
.LBB0_1098:
	s_xor_b64 s[30:31], s[0:1], -1
	s_and_b64 s[0:1], s[0:1], exec
	s_cselect_b32 s1, s19, s37
	v_mov_b32_e32 v174, v190
	s_lshl_b32 s14, s1, 15
	s_lshl_b32 s0, s1, 16
	s_add_u32 s4, s16, s0
	v_readfirstlane_b32 s7, v174
	s_addc_u32 s5, s17, 0
	s_ashr_i32 s0, s7, 6
	v_lshlrev_b32_e32 v1, 3, v174
	s_lshl_b32 s6, s1, 8
	s_lshl_b32 s38, s1, 2
	s_ashr_i32 s1, s0, 31
	v_ashrrev_i32_e32 v0, 4, v174
	v_and_b32_e32 v2, 0x78, v1
	v_and_b32_e32 v175, 31, v174
	v_bfe_u32 v176, v174, 5, 1
	s_lshl_b32 s39, s0, 5
	s_and_b32 s7, s7, 0x3fffffc0
	s_lshl_b64 s[28:29], s[0:1], 13
	v_lshlrev_b32_e32 v2, 1, v2
	v_lshlrev_b32_e32 v3, 8, v0
	v_lshlrev_b32_e32 v10, 8, v175
	v_lshlrev_b32_e32 v11, 4, v176
	s_add_u32 s0, s4, s28
	v_or_b32_e32 v148, v2, v3
	v_or_b32_e32 v12, v11, v10
	s_addc_u32 s1, s5, s29
	global_load_dwordx4 v[96:99], v148, s[22:23]
	global_load_dwordx4 v[100:103], v148, s[20:21]
	global_load_dwordx4 v[136:139], v148, s[42:43]
	global_load_dwordx4 v[140:143], v148, s[26:27]
	global_load_dwordx4 v[104:107], v12, s[0:1]
	global_load_dwordx4 v[108:111], v12, s[0:1] offset:32
	global_load_dwordx4 v[112:115], v12, s[0:1] offset:64
	global_load_dwordx4 v[116:119], v12, s[0:1] offset:96
	global_load_dwordx4 v[120:123], v12, s[0:1] offset:128
	global_load_dwordx4 v[124:127], v12, s[0:1] offset:160
	global_load_dwordx4 v[128:131], v12, s[0:1] offset:192
	global_load_dwordx4 v[132:135], v12, s[0:1] offset:224
	v_and_b32_e32 v6, 0xfffff0, v0
	v_lshlrev_b32_e32 v7, 1, v0
	v_and_or_b32 v6, v7, 8, v6
	v_lshrrev_b32_e32 v7, 1, v0
	v_and_b32_e32 v8, 3, v0
	v_add_u32_e32 v0, 32, v0
	v_and_b32_e32 v4, 63, v174
	v_and_b32_e32 v9, 0xfffff0, v0
	v_lshlrev_b32_e32 v0, 1, v0
	v_lshlrev_b32_e32 v12, 4, v174
	s_lshl_b32 s0, s7, 2
	v_and_or_b32 v0, v0, 8, v9
	v_lshlrev_b32_e32 v9, 3, v4
	v_and_b32_e32 v13, 0xc0, v12
	v_lshlrev_b32_e32 v14, 1, v174
	s_add_i32 s0, s0, 0
	v_lshlrev_b32_e32 v5, 2, v176
	v_and_or_b32 v13, v9, 24, v13
	v_and_b32_e32 v14, 32, v14
	v_and_b32_e32 v9, 0x100, v9
	s_add_i32 s18, s38, 4
	s_add_i32 s39, s39, s6
	s_add_i32 s4, s0, 0x10000
	v_lshrrev_b32_e32 v6, 1, v6
	v_bfe_u32 v1, v1, 5, 2
	v_lshrrev_b32_e32 v0, 1, v0
	v_or3_b32 v9, v13, v14, v9
	v_subrev_u32_e32 v13, s6, v5
	s_cmp_lg_u32 0, -1
	v_or_b32_e32 v6, v6, v1
	v_and_or_b32 v7, v7, 4, v8
	v_or_b32_e32 v0, v0, v1
	v_and_b32_e32 v1, 0x70, v174
	v_cvt_f32_i32_e32 v13, v13
	s_cselect_b32 s0, 0, 0
	v_lshlrev_b32_e32 v6, 9, v6
	v_lshlrev_b32_e32 v7, 6, v7
	v_and_b32_e32 v8, 48, v2
	v_lshlrev_b32_e32 v0, 9, v0
	v_bitop3_b32 v1, v2, v3, v1 bitop3:0xde
	v_add_u32_e32 v178, s0, v9
	s_movk_i32 s0, 0x70
	v_or3_b32 v0, v0, v7, v8
	v_or3_b32 v6, v6, v7, v8
	v_add_u32_e32 v182, 0, v1
	v_bfe_u32 v200, v174, 7, 1
	v_lshlrev_b32_e32 v200, 7, v200
	v_xor_b32_e32 v182, v182, v200
	v_and_b32_e32 v1, 0x70, v12
	v_bitop3_b32 v2, v11, v12, s0 bitop3:0x78
	s_movk_i32 s0, 0x60
	s_waitcnt vmcnt(0)
	v_add_u32_e32 v180, 0, v6
	v_add_u32_e32 v181, 0, v0
	v_add_u32_e32 v0, 0, v10
	v_bitop3_b32 v3, v11, v1, 32 bitop3:0x36
	v_bitop3_b32 v6, v11, v1, 64 bitop3:0x36
	v_bitop3_b32 v1, v11, v1, s0 bitop3:0x36
	v_cmp_gt_u32_e64 s[0:1], 32, v4
	v_or_b32_e32 v4, s39, v175
	v_mov_b32_e32 v32, v149
	v_mov_b32_e32 v33, v149
	v_mov_b32_e32 v46, v149
	v_mov_b32_e32 v47, v149
	v_mul_f32_e32 v179, v172, v13
	v_add_u32_e32 v177, s4, v11
	v_sub_u32_e32 v184, v4, v5
	v_mov_b32_e32 v34, v149
	v_mov_b32_e32 v35, v149
	v_mov_b32_e32 v36, v149
	v_mov_b32_e32 v37, v149
	v_mov_b32_e32 v38, v149
	v_mov_b32_e32 v39, v149
	v_mov_b32_e32 v40, v149
	v_mov_b32_e32 v41, v149
	v_mov_b32_e32 v42, v149
	v_mov_b32_e32 v43, v149
	v_mov_b32_e32 v44, v149
	v_mov_b32_e32 v45, v149
	v_add_u32_e32 v186, v0, v2
	v_add_u32_e32 v187, v0, v3
	v_add_u32_e32 v188, v0, v6
	v_add_u32_e32 v189, v0, v1
	v_bfe_u32 v200, v174, 3, 1
	v_lshlrev_b32_e32 v200, 7, v200
	v_xor_b32_e32 v186, v186, v200
	v_xor_b32_e32 v187, v187, v200
	v_xor_b32_e32 v188, v188, v200
	v_xor_b32_e32 v189, v189, v200
	v_mov_b64_e32 v[62:63], v[46:47]
	v_mov_b64_e32 v[16:17], v[32:33]
	v_mov_b64_e32 v[0:1], v[32:33]
	s_mov_b32 s12, 0
	v_lshl_add_u32 v183, v175, 2, s4
	v_mov_b32_e32 v203, 0xf149f2ca
	v_mov_b32_e32 v185, 0
	s_movk_i32 s13, 0x7f
	s_mov_b64 s[46:47], s[2:3]
	s_mov_b64 s[40:41], s[24:25]
	v_mov_b64_e32 v[60:61], v[44:45]
	v_mov_b64_e32 v[58:59], v[42:43]
	v_mov_b64_e32 v[56:57], v[40:41]
	v_mov_b64_e32 v[54:55], v[38:39]
	v_mov_b64_e32 v[52:53], v[36:37]
	v_mov_b64_e32 v[50:51], v[34:35]
	v_mov_b64_e32 v[48:49], v[32:33]
	v_mov_b64_e32 v[18:19], v[34:35]
	v_mov_b64_e32 v[20:21], v[36:37]
	v_mov_b64_e32 v[22:23], v[38:39]
	v_mov_b64_e32 v[24:25], v[40:41]
	v_mov_b64_e32 v[26:27], v[42:43]
	v_mov_b64_e32 v[28:29], v[44:45]
	v_mov_b64_e32 v[30:31], v[46:47]
	v_mov_b64_e32 v[2:3], v[34:35]
	v_mov_b64_e32 v[4:5], v[36:37]
	v_mov_b64_e32 v[6:7], v[38:39]
	v_mov_b64_e32 v[8:9], v[40:41]
	v_mov_b64_e32 v[10:11], v[42:43]
	v_mov_b64_e32 v[12:13], v[44:45]
	v_mov_b64_e32 v[14:15], v[46:47]
	s_waitcnt vmcnt(11)
	ds_write_b128 v180, v[96:99]
	s_waitcnt vmcnt(10)
	ds_write_b128 v181, v[100:103]
	s_waitcnt vmcnt(9)
	ds_write_b128 v182, v[136:139] offset:32768
	s_waitcnt vmcnt(8)
	ds_write_b128 v182, v[140:143] offset:40960
	s_waitcnt lgkmcnt(0)
	s_barrier
	v_add_u32_e32 v168, 0x4000, v148
	global_load_dwordx4 v[136:139], v168, s[42:43]
	global_load_dwordx4 v[140:143], v168, s[26:27]
	v_add_u32_e32 v169, 0x4000, v168
	s_mov_b32 s13, 0
	s_mov_b32 s12, 0
	s_mov_b32 s10, 0x3e0293ee
	s_mov_b32 s6, 0x11000
	s_mov_b32 s7, 0
	s_mov_b32 s8, 0x4000
	ds_read_b128 v[236:239], v186 offset:32768
	ds_read_b128 v[240:243], v186 offset:40960
	v_mov_b32_e32 v244, 0
	v_mov_b32_e32 v245, 0
	v_mov_b32_e32 v246, 0
	v_mov_b32_e32 v247, 0
	v_add_u32_e32 v200, s6, v180
	v_add_u32_e32 v201, s6, v181
	ds_write_b128 v200, v[244:247]
	ds_write_b128 v201, v[244:247]
	ds_read_b128 v[244:247], v187 offset:32768
	v_mov_b32_e32 v204, 0
	v_mov_b32_e32 v205, 0
	v_mov_b32_e32 v206, 0
	v_mov_b32_e32 v207, 0
	v_mov_b32_e32 v208, 0
	v_mov_b32_e32 v209, 0
	v_mov_b32_e32 v210, 0
	v_mov_b32_e32 v211, 0
	v_mov_b32_e32 v212, 0
	v_mov_b32_e32 v213, 0
	v_mov_b32_e32 v214, 0
	v_mov_b32_e32 v215, 0
	v_mov_b32_e32 v216, 0
	v_mov_b32_e32 v217, 0
	v_mov_b32_e32 v218, 0
	v_mov_b32_e32 v219, 0
	v_cvt_f32_u32_e32 v64, s13
	v_mov_b32_e32 v165, v164
	v_fma_f32 v64, v172, v64, v179
	v_add_f32_e32 v68, v173, v64
	v_add_f32_e32 v72, v173, v68
	v_add_f32_e32 v76, v173, v72
	v_add_f32_e32 v65, v172, v64
	v_add_f32_e32 v69, v172, v68
	v_add_f32_e32 v73, v172, v72
	v_add_f32_e32 v77, v172, v76
	v_pk_add_f32 v[66:67], v[162:163], v[64:65] op_sel_hi:[1,0]
	v_pk_add_f32 v[70:71], v[162:163], v[68:69] op_sel_hi:[1,0]
	v_pk_add_f32 v[74:75], v[162:163], v[72:73] op_sel_hi:[1,0]
	v_pk_add_f32 v[78:79], v[162:163], v[76:77] op_sel_hi:[1,0]
	v_pk_add_f32 v[82:83], v[164:165], v[66:67]
	v_pk_add_f32 v[80:81], v[166:167], v[64:65]
	v_pk_add_f32 v[86:87], v[164:165], v[70:71]
	v_pk_add_f32 v[84:85], v[164:165], v[68:69]
	v_pk_add_f32 v[90:91], v[164:165], v[74:75]
	v_pk_add_f32 v[88:89], v[164:165], v[72:73]
	v_pk_add_f32 v[94:95], v[164:165], v[78:79]
	v_pk_add_f32 v[92:93], v[164:165], v[76:77]
	s_addk_i32 s13, 0x40
	s_waitcnt lgkmcnt(3)
	v_mfma_f32_32x32x16_bf16 v[64:79], v[236:239], v[104:107], v[64:79]
	ds_read_b128 v[236:239], v187 offset:40960
	s_waitcnt lgkmcnt(3)
	v_mfma_f32_32x32x16_bf16 v[80:95], v[240:243], v[104:107], v[80:95]
	ds_read_b128 v[240:243], v188 offset:32768
	s_waitcnt lgkmcnt(2)
	v_mfma_f32_32x32x16_bf16 v[64:79], v[244:247], v[108:111], v[64:79]
	ds_read_b128 v[244:247], v188 offset:40960
	s_waitcnt lgkmcnt(2)
	v_mfma_f32_32x32x16_bf16 v[80:95], v[236:239], v[108:111], v[80:95]
	ds_read_b128 v[236:239], v189 offset:32768
	s_waitcnt lgkmcnt(2)
	v_mfma_f32_32x32x16_bf16 v[64:79], v[240:243], v[112:115], v[64:79]
	ds_read_b128 v[240:243], v189 offset:40960
	s_waitcnt lgkmcnt(2)
	v_mfma_f32_32x32x16_bf16 v[80:95], v[244:247], v[112:115], v[80:95]
	v_xor_b32_e32 v186, 0x80, v186
	v_xor_b32_e32 v187, 0x80, v187
	v_xor_b32_e32 v188, 0x80, v188
	v_xor_b32_e32 v189, 0x80, v189
	ds_read_b128 v[244:247], v186 offset:32768
	s_waitcnt lgkmcnt(2)
	v_mfma_f32_32x32x16_bf16 v[64:79], v[236:239], v[116:119], v[64:79]
	ds_read_b128 v[236:239], v186 offset:40960
	s_waitcnt lgkmcnt(2)
	v_mfma_f32_32x32x16_bf16 v[80:95], v[240:243], v[116:119], v[80:95]
	ds_read_b128 v[240:243], v187 offset:32768
	s_waitcnt lgkmcnt(2)
	v_mfma_f32_32x32x16_bf16 v[64:79], v[244:247], v[120:123], v[64:79]
	ds_read_b128 v[244:247], v187 offset:40960
	s_waitcnt lgkmcnt(2)
	v_mfma_f32_32x32x16_bf16 v[80:95], v[236:239], v[120:123], v[80:95]
	ds_read_b128 v[236:239], v188 offset:32768
	s_waitcnt lgkmcnt(2)
	v_mfma_f32_32x32x16_bf16 v[64:79], v[240:243], v[124:127], v[64:79]
	ds_read_b128 v[240:243], v188 offset:40960
	s_waitcnt lgkmcnt(2)
	v_mfma_f32_32x32x16_bf16 v[80:95], v[244:247], v[124:127], v[80:95]
	ds_read_b128 v[244:247], v189 offset:32768
	s_waitcnt lgkmcnt(2)
	v_mfma_f32_32x32x16_bf16 v[64:79], v[236:239], v[128:131], v[64:79]
	ds_read_b128 v[236:239], v189 offset:40960
	s_waitcnt lgkmcnt(2)
	v_mfma_f32_32x32x16_bf16 v[80:95], v[240:243], v[128:131], v[80:95]
	s_waitcnt lgkmcnt(1)
	v_mfma_f32_32x32x16_bf16 v[64:79], v[244:247], v[132:135], v[64:79]
	s_waitcnt lgkmcnt(0)
	v_mfma_f32_32x32x16_bf16 v[80:95], v[236:239], v[132:135], v[80:95]
	s_waitcnt vmcnt(0)
	ds_write_b128 v182, v[136:139] offset:49152
	ds_write_b128 v182, v[140:143] offset:57344
	s_waitcnt lgkmcnt(0)
	s_barrier
	.p2alignl 6, 3212836864

.Lat_nre:
	s_waitcnt lgkmcnt(0)
	s_barrier
	v_xor_b32_e32 v186, 0x80, v186
	v_xor_b32_e32 v187, 0x80, v187
	v_xor_b32_e32 v188, 0x80, v188
	v_xor_b32_e32 v189, 0x80, v189
	ds_read_b128 v[236:239], v186 offset:49152
	ds_read_b128 v[240:243], v186 offset:57344
	ds_read_b128 v[244:247], v187 offset:49152
	v_cvt_f32_u32_e32 v204, s13
	v_mov_b32_e32 v165, v164
	v_fma_f32 v204, v172, v204, v179
	v_add_f32_e32 v208, v173, v204
	v_add_f32_e32 v212, v173, v208
	v_add_f32_e32 v216, v173, v212
	v_add_f32_e32 v205, v172, v204
	v_add_f32_e32 v209, v172, v208
	v_add_f32_e32 v213, v172, v212
	v_add_f32_e32 v217, v172, v216
	v_pk_add_f32 v[206:207], v[162:163], v[204:205] op_sel_hi:[1,0]
	v_pk_add_f32 v[210:211], v[162:163], v[208:209] op_sel_hi:[1,0]
	v_pk_add_f32 v[214:215], v[162:163], v[212:213] op_sel_hi:[1,0]
	v_pk_add_f32 v[218:219], v[162:163], v[216:217] op_sel_hi:[1,0]
	v_pk_add_f32 v[222:223], v[164:165], v[206:207]
	v_pk_add_f32 v[220:221], v[166:167], v[204:205]
	v_pk_add_f32 v[226:227], v[164:165], v[210:211]
	v_pk_add_f32 v[224:225], v[164:165], v[208:209]
	v_pk_add_f32 v[230:231], v[164:165], v[214:215]
	v_pk_add_f32 v[228:229], v[164:165], v[212:213]
	v_pk_add_f32 v[234:235], v[164:165], v[218:219]
	v_pk_add_f32 v[232:233], v[164:165], v[216:217]
	s_addk_i32 s13, 0x40
	v_exp_f32_e32 v80, v80
	s_waitcnt lgkmcnt(2)
	v_mfma_f32_32x32x16_bf16 v[204:219], v[236:239], v[104:107], v[204:219]
	ds_read_b128 v[236:239], v187 offset:57344
	v_exp_f32_e32 v81, v81
	v_pk_add_f32 v[170:171], v[170:171], v[78:79]
	v_exp_f32_e32 v82, v82
	s_waitcnt lgkmcnt(2)
	v_mfma_f32_32x32x16_bf16 v[220:235], v[240:243], v[104:107], v[220:235]
	ds_read_b128 v[240:243], v188 offset:49152
	v_exp_f32_e32 v83, v83
	v_pk_add_f32 v[170:171], v[170:171], v[80:81]
	v_exp_f32_e32 v84, v84
	v_exp_f32_e32 v85, v85
	s_waitcnt lgkmcnt(2)
	v_mfma_f32_32x32x16_bf16 v[204:219], v[244:247], v[108:111], v[204:219]
	ds_read_b128 v[244:247], v188 offset:57344
	v_pk_add_f32 v[170:171], v[170:171], v[82:83]
	v_exp_f32_e32 v86, v86
	v_exp_f32_e32 v87, v87
	s_waitcnt lgkmcnt(2)
	v_mfma_f32_32x32x16_bf16 v[220:235], v[236:239], v[108:111], v[220:235]
	ds_read_b128 v[236:239], v189 offset:49152
	v_pk_add_f32 v[170:171], v[170:171], v[84:85]
	v_exp_f32_e32 v88, v88
	v_exp_f32_e32 v89, v89
	v_pk_add_f32 v[170:171], v[170:171], v[86:87]
	s_waitcnt lgkmcnt(2)
	v_mfma_f32_32x32x16_bf16 v[204:219], v[240:243], v[112:115], v[204:219]
	ds_read_b128 v[240:243], v189 offset:57344
	v_exp_f32_e32 v90, v90
	v_exp_f32_e32 v91, v91
	v_pk_add_f32 v[170:171], v[170:171], v[88:89]
	v_exp_f32_e32 v92, v92
	s_waitcnt lgkmcnt(2)
	v_mfma_f32_32x32x16_bf16 v[220:235], v[244:247], v[112:115], v[220:235]
	v_xor_b32_e32 v186, 0x80, v186
	v_xor_b32_e32 v187, 0x80, v187
	v_xor_b32_e32 v188, 0x80, v188
	v_xor_b32_e32 v189, 0x80, v189
	ds_read_b128 v[244:247], v186 offset:49152
	v_exp_f32_e32 v93, v93
	v_pk_add_f32 v[170:171], v[170:171], v[90:91]
	v_exp_f32_e32 v94, v94
	s_waitcnt lgkmcnt(2)
	v_mfma_f32_32x32x16_bf16 v[204:219], v[236:239], v[116:119], v[204:219]
	ds_read_b128 v[236:239], v186 offset:57344
	v_exp_f32_e32 v95, v95
	v_pk_add_f32 v[170:171], v[170:171], v[92:93]
	s_nop 0
	v_pk_add_f32 v[170:171], v[170:171], v[94:95]
	s_waitcnt lgkmcnt(2)
	v_mfma_f32_32x32x16_bf16 v[220:235], v[240:243], v[116:119], v[220:235]
	ds_read_b128 v[240:243], v187 offset:49152
	v_add_f32_e32 v249, v170, v171
	v_mov_b32_e32 v170, v249
	s_nop 1
	s_waitcnt lgkmcnt(2)
	v_mfma_f32_32x32x16_bf16 v[204:219], v[244:247], v[120:123], v[204:219]
	ds_read_b128 v[244:247], v187 offset:57344
	v_permlane32_swap_b32_e32 v249, v170
	v_cvt_pk_bf16_f32 v64, v64, v65
	v_cvt_pk_bf16_f32 v65, v66, v67
	v_cvt_pk_bf16_f32 v66, v68, v69
	s_waitcnt lgkmcnt(2)
	v_mfma_f32_32x32x16_bf16 v[220:235], v[236:239], v[120:123], v[220:235]
	ds_read_b128 v[236:239], v188 offset:49152
	v_cvt_pk_bf16_f32 v67, v70, v71
	v_cvt_pk_bf16_f32 v68, v72, v73
	v_cvt_pk_bf16_f32 v69, v74, v75
	s_waitcnt lgkmcnt(2)
	v_mfma_f32_32x32x16_bf16 v[204:219], v[240:243], v[124:127], v[204:219]
	ds_read_b128 v[240:243], v188 offset:57344
	v_cvt_pk_bf16_f32 v70, v76, v77
	v_cvt_pk_bf16_f32 v71, v78, v79
	v_cvt_pk_bf16_f32 v72, v80, v81
	v_cvt_pk_bf16_f32 v73, v82, v83
	s_waitcnt lgkmcnt(2)
	v_mfma_f32_32x32x16_bf16 v[220:235], v[244:247], v[124:127], v[220:235]
	ds_read_b128 v[244:247], v189 offset:49152
	v_cvt_pk_bf16_f32 v74, v84, v85
	v_cvt_pk_bf16_f32 v75, v86, v87
	v_cvt_pk_bf16_f32 v76, v88, v89
	s_waitcnt lgkmcnt(2)
	v_mfma_f32_32x32x16_bf16 v[204:219], v[236:239], v[128:131], v[204:219]
	ds_read_b128 v[236:239], v189 offset:57344
	v_cvt_pk_bf16_f32 v77, v90, v91
	v_cvt_pk_bf16_f32 v78, v92, v93
	v_cvt_pk_bf16_f32 v79, v94, v95
	v_permlane32_swap_b32_e32 v64, v66
	s_waitcnt lgkmcnt(2)
	v_mfma_f32_32x32x16_bf16 v[220:235], v[240:243], v[128:131], v[220:235]
	v_permlane32_swap_b32_e32 v65, v67
	v_permlane32_swap_b32_e32 v68, v70
	v_permlane32_swap_b32_e32 v69, v71
	v_permlane32_swap_b32_e32 v72, v74
	s_waitcnt lgkmcnt(1)
	v_mfma_f32_32x32x16_bf16 v[204:219], v[244:247], v[132:135], v[204:219]
	v_permlane32_swap_b32_e32 v73, v75
	v_permlane32_swap_b32_e32 v76, v78
	v_permlane32_swap_b32_e32 v77, v79
	s_waitcnt lgkmcnt(0)
	v_mfma_f32_32x32x16_bf16 v[220:235], v[236:239], v[132:135], v[220:235]
	v_add_f32_e32 v171, v249, v170
	v_fmac_f32_e32 v171, v185, v202
	v_mov_b32_e32 v185, v171
	s_waitcnt vmcnt(0)
	v_add_u32_e32 v200, s8, v180
	v_add_u32_e32 v201, s8, v181
	ds_write_b128 v200, v[96:99]
	ds_write_b128 v201, v[100:103]
	s_and_b64 vcc, exec, s[34:35]
	s_cbranch_vccz .Lat_nwe
	ds_write_b128 v182, v[136:139] offset:32768
	ds_write_b128 v182, v[140:143] offset:40960

.Lat_nro:
	s_waitcnt lgkmcnt(0)
	s_barrier
	v_xor_b32_e32 v186, 0x80, v186
	v_xor_b32_e32 v187, 0x80, v187
	v_xor_b32_e32 v188, 0x80, v188
	v_xor_b32_e32 v189, 0x80, v189
	ds_read_b128 v[236:239], v186 offset:32768
	ds_read_b128 v[240:243], v186 offset:40960
	ds_read_b128 v[244:247], v187 offset:32768
	v_cvt_f32_u32_e32 v64, s13
	v_mov_b32_e32 v165, v164
	v_fma_f32 v64, v172, v64, v179
	v_add_f32_e32 v68, v173, v64
	v_add_f32_e32 v72, v173, v68
	v_add_f32_e32 v76, v173, v72
	v_add_f32_e32 v65, v172, v64
	v_add_f32_e32 v69, v172, v68
	v_add_f32_e32 v73, v172, v72
	v_add_f32_e32 v77, v172, v76
	v_pk_add_f32 v[66:67], v[162:163], v[64:65] op_sel_hi:[1,0]
	v_pk_add_f32 v[70:71], v[162:163], v[68:69] op_sel_hi:[1,0]
	v_pk_add_f32 v[74:75], v[162:163], v[72:73] op_sel_hi:[1,0]
	v_pk_add_f32 v[78:79], v[162:163], v[76:77] op_sel_hi:[1,0]
	v_pk_add_f32 v[82:83], v[164:165], v[66:67]
	v_pk_add_f32 v[80:81], v[166:167], v[64:65]
	v_pk_add_f32 v[86:87], v[164:165], v[70:71]
	v_pk_add_f32 v[84:85], v[164:165], v[68:69]
	v_pk_add_f32 v[90:91], v[164:165], v[74:75]
	v_pk_add_f32 v[88:89], v[164:165], v[72:73]
	v_pk_add_f32 v[94:95], v[164:165], v[78:79]
	v_pk_add_f32 v[92:93], v[164:165], v[76:77]
	s_addk_i32 s13, 0x40
	v_exp_f32_e32 v220, v220
	s_waitcnt lgkmcnt(2)
	v_mfma_f32_32x32x16_bf16 v[64:79], v[236:239], v[104:107], v[64:79]
	ds_read_b128 v[236:239], v187 offset:40960
	v_exp_f32_e32 v221, v221
	v_pk_add_f32 v[170:171], v[170:171], v[218:219]
	v_exp_f32_e32 v222, v222
	s_waitcnt lgkmcnt(2)
	v_mfma_f32_32x32x16_bf16 v[80:95], v[240:243], v[104:107], v[80:95]
	ds_read_b128 v[240:243], v188 offset:32768
	v_exp_f32_e32 v223, v223
	v_pk_add_f32 v[170:171], v[170:171], v[220:221]
	v_exp_f32_e32 v224, v224
	v_exp_f32_e32 v225, v225
	s_waitcnt lgkmcnt(2)
	v_mfma_f32_32x32x16_bf16 v[64:79], v[244:247], v[108:111], v[64:79]
	ds_read_b128 v[244:247], v188 offset:40960
	v_pk_add_f32 v[170:171], v[170:171], v[222:223]
	v_exp_f32_e32 v226, v226
	v_exp_f32_e32 v227, v227
	s_waitcnt lgkmcnt(2)
	v_mfma_f32_32x32x16_bf16 v[80:95], v[236:239], v[108:111], v[80:95]
	ds_read_b128 v[236:239], v189 offset:32768
	v_pk_add_f32 v[170:171], v[170:171], v[224:225]
	v_exp_f32_e32 v228, v228
	v_exp_f32_e32 v229, v229
	v_pk_add_f32 v[170:171], v[170:171], v[226:227]
	s_waitcnt lgkmcnt(2)
	v_mfma_f32_32x32x16_bf16 v[64:79], v[240:243], v[112:115], v[64:79]
	ds_read_b128 v[240:243], v189 offset:40960
	v_exp_f32_e32 v230, v230
	v_exp_f32_e32 v231, v231
	v_pk_add_f32 v[170:171], v[170:171], v[228:229]
	v_exp_f32_e32 v232, v232
	s_waitcnt lgkmcnt(2)
	v_mfma_f32_32x32x16_bf16 v[80:95], v[244:247], v[112:115], v[80:95]
	v_xor_b32_e32 v186, 0x80, v186
	v_xor_b32_e32 v187, 0x80, v187
	v_xor_b32_e32 v188, 0x80, v188
	v_xor_b32_e32 v189, 0x80, v189
	ds_read_b128 v[244:247], v186 offset:32768
	v_exp_f32_e32 v233, v233
	v_pk_add_f32 v[170:171], v[170:171], v[230:231]
	v_exp_f32_e32 v234, v234
	s_waitcnt lgkmcnt(2)
	v_mfma_f32_32x32x16_bf16 v[64:79], v[236:239], v[116:119], v[64:79]
	ds_read_b128 v[236:239], v186 offset:40960
	v_exp_f32_e32 v235, v235
	v_pk_add_f32 v[170:171], v[170:171], v[232:233]
	s_nop 0
	v_pk_add_f32 v[170:171], v[170:171], v[234:235]
	s_waitcnt lgkmcnt(2)
	v_mfma_f32_32x32x16_bf16 v[80:95], v[240:243], v[116:119], v[80:95]
	ds_read_b128 v[240:243], v187 offset:32768
	v_add_f32_e32 v249, v170, v171
	v_mov_b32_e32 v170, v249
	s_nop 1
	s_waitcnt lgkmcnt(2)
	v_mfma_f32_32x32x16_bf16 v[64:79], v[244:247], v[120:123], v[64:79]
	ds_read_b128 v[244:247], v187 offset:40960
	v_permlane32_swap_b32_e32 v249, v170
	v_cvt_pk_bf16_f32 v204, v204, v205
	v_cvt_pk_bf16_f32 v205, v206, v207
	v_cvt_pk_bf16_f32 v206, v208, v209
	s_waitcnt lgkmcnt(2)
	v_mfma_f32_32x32x16_bf16 v[80:95], v[236:239], v[120:123], v[80:95]
	ds_read_b128 v[236:239], v188 offset:32768
	v_cvt_pk_bf16_f32 v207, v210, v211
	v_cvt_pk_bf16_f32 v208, v212, v213
	v_cvt_pk_bf16_f32 v209, v214, v215
	s_waitcnt lgkmcnt(2)
	v_mfma_f32_32x32x16_bf16 v[64:79], v[240:243], v[124:127], v[64:79]
	ds_read_b128 v[240:243], v188 offset:40960
	v_cvt_pk_bf16_f32 v210, v216, v217
	v_cvt_pk_bf16_f32 v211, v218, v219
	v_cvt_pk_bf16_f32 v212, v220, v221
	v_cvt_pk_bf16_f32 v213, v222, v223
	s_waitcnt lgkmcnt(2)
	v_mfma_f32_32x32x16_bf16 v[80:95], v[244:247], v[124:127], v[80:95]
	ds_read_b128 v[244:247], v189 offset:32768
	v_cvt_pk_bf16_f32 v214, v224, v225
	v_cvt_pk_bf16_f32 v215, v226, v227
	v_cvt_pk_bf16_f32 v216, v228, v229
	s_waitcnt lgkmcnt(2)
	v_mfma_f32_32x32x16_bf16 v[64:79], v[236:239], v[128:131], v[64:79]
	ds_read_b128 v[236:239], v189 offset:40960
	v_cvt_pk_bf16_f32 v217, v230, v231
	v_cvt_pk_bf16_f32 v218, v232, v233
	v_cvt_pk_bf16_f32 v219, v234, v235
	v_permlane32_swap_b32_e32 v204, v206
	s_waitcnt lgkmcnt(2)
	v_mfma_f32_32x32x16_bf16 v[80:95], v[240:243], v[128:131], v[80:95]
	v_permlane32_swap_b32_e32 v205, v207
	v_permlane32_swap_b32_e32 v208, v210
	v_permlane32_swap_b32_e32 v209, v211
	v_permlane32_swap_b32_e32 v212, v214
	s_waitcnt lgkmcnt(1)
	v_mfma_f32_32x32x16_bf16 v[64:79], v[244:247], v[132:135], v[64:79]
	v_permlane32_swap_b32_e32 v213, v215
	v_permlane32_swap_b32_e32 v216, v218
	v_permlane32_swap_b32_e32 v217, v219
	s_waitcnt lgkmcnt(0)
	v_mfma_f32_32x32x16_bf16 v[80:95], v[236:239], v[132:135], v[80:95]
	v_add_f32_e32 v171, v249, v170
	v_fmac_f32_e32 v171, v185, v202
	v_mov_b32_e32 v185, v171
	s_waitcnt vmcnt(0)
	s_and_b64 vcc, exec, s[34:35]
	s_cbranch_vccz .Lat_nwo
	v_add_u32_e32 v200, s8, v180
	v_add_u32_e32 v201, s8, v181
	ds_write_b128 v200, v[96:99]
	ds_write_b128 v201, v[100:103]
	ds_write_b128 v182, v[136:139] offset:49152
	ds_write_b128 v182, v[140:143] offset:57344
